# scanC/scanA: LDS fragment reads issued ahead of the MFMA chains (counted lgkmcnt), barrier and accumulation order unchanged
# speedup vs baseline: 1.0032x; 1.0011x over previous
.LBB0_300:
	s_or_b64 exec, exec, s[2:3]
	v_cndmask_b32_e64 v18, 0, v18, s[4:5]
	v_add_f32_e32 v19, v19, v18
	v_cndmask_b32_e64 v18, v18, v19, s[6:7]
	v_add_f32_e32 v16, v16, v18
	v_cndmask_b32_e64 v16, v18, v16, s[8:9]
	v_add_f32_e32 v17, v17, v16
	v_cndmask_b32_e64 v221, v16, v17, s[10:11]
	v_add_f32_e32 v16, v221, v23
	v_add_f32_e32 v17, v220, v221
	v_mul_f32_e32 v16, 0x3fb8aa3b, v16
	v_mul_f32_e32 v17, 0x3fb8aa3b, v17
	v_exp_f32_e32 v16, v16
	v_exp_f32_e32 v17, v17
	v_lshlrev_b32_e32 v161, 16, v161
	v_lshlrev_b32_e32 v163, 16, v163
	v_rcp_f32_e32 v18, v16
	v_rcp_f32_e32 v19, v17
	v_mul_f32_e32 v16, v16, v161
	v_cvt_pk_bf16_f32 v16, v16, v177
	ds_write_b16 v106, v16
	v_mul_f32_e32 v16, v17, v163
	v_lshlrev_b32_e32 v162, 16, v162
	v_lshlrev_b32_e32 v164, 16, v164
	v_cvt_pk_bf16_f32 v16, v16, v177
	ds_write_b16 v106, v16 offset:272
	v_mul_f32_e32 v16, v18, v162
	v_mul_f32_e32 v17, v19, v164
	v_cvt_pk_bf16_f32 v18, v16, v177
	ds_write_b16 v106, v18 offset:17408
	v_cvt_pk_bf16_f32 v18, v17, v177
	v_mul_f32_e32 v16, v20, v16
	v_mul_f32_e32 v17, v20, v17
	ds_write_b16 v106, v18 offset:17680
	v_cvt_pk_bf16_f32 v16, v16, v17
	v_add_f32_e32 v17, v218, v221
	v_add_f32_e32 v18, v219, v221
	v_mul_f32_e32 v17, 0x3fb8aa3b, v17
	v_mul_f32_e32 v18, 0x3fb8aa3b, v18
	v_exp_f32_e32 v17, v17
	v_exp_f32_e32 v18, v18
	v_lshlrev_b32_e32 v167, 16, v167
	v_lshlrev_b32_e32 v169, 16, v169
	v_rcp_f32_e32 v19, v17
	v_rcp_f32_e32 v23, v18
	v_mul_f32_e32 v17, v17, v167
	v_cvt_pk_bf16_f32 v17, v17, v177
	ds_write_b16 v107, v17
	v_mul_f32_e32 v17, v18, v169
	v_lshlrev_b32_e32 v168, 16, v168
	v_lshlrev_b32_e32 v170, 16, v170
	v_cvt_pk_bf16_f32 v17, v17, v177
	ds_write_b16 v107, v17 offset:272
	v_mul_f32_e32 v17, v19, v168
	v_mul_f32_e32 v18, v23, v170
	v_cvt_pk_bf16_f32 v19, v17, v177
	ds_write_b16 v107, v19 offset:17408
	v_cvt_pk_bf16_f32 v19, v18, v177
	v_mul_f32_e32 v17, v20, v17
	v_mul_f32_e32 v18, v20, v18
	ds_write_b16 v107, v19 offset:17680
	v_cvt_pk_bf16_f32 v17, v17, v18
	v_add_f32_e32 v18, v201, v221
	v_add_f32_e32 v19, v213, v221
	v_mul_f32_e32 v18, 0x3fb8aa3b, v18
	v_mul_f32_e32 v19, 0x3fb8aa3b, v19
	v_exp_f32_e32 v18, v18
	v_exp_f32_e32 v19, v19
	v_lshlrev_b32_e32 v171, 16, v171
	v_lshlrev_b32_e32 v173, 16, v173
	v_rcp_f32_e32 v23, v18
	v_rcp_f32_e32 v161, v19
	v_mul_f32_e32 v18, v18, v171
	v_cvt_pk_bf16_f32 v18, v18, v177
	ds_write_b16 v108, v18
	v_mul_f32_e32 v18, v19, v173
	v_lshlrev_b32_e32 v172, 16, v172
	v_lshlrev_b32_e32 v174, 16, v174
	v_cvt_pk_bf16_f32 v18, v18, v177
	ds_write_b16 v108, v18 offset:272
	v_mul_f32_e32 v18, v23, v172
	v_mul_f32_e32 v19, v161, v174
	v_cvt_pk_bf16_f32 v23, v18, v177
	ds_write_b16 v108, v23 offset:17408
	v_cvt_pk_bf16_f32 v23, v19, v177
	v_mul_f32_e32 v18, v20, v18
	v_mul_f32_e32 v19, v20, v19
	ds_write_b16 v108, v23 offset:17680
	v_cvt_pk_bf16_f32 v18, v18, v19
	v_add_f32_e32 v19, v191, v221
	v_add_f32_e32 v23, v192, v221
	v_mul_f32_e32 v19, 0x3fb8aa3b, v19
	v_mul_f32_e32 v23, 0x3fb8aa3b, v23
	v_exp_f32_e32 v19, v19
	v_exp_f32_e32 v23, v23
	v_lshlrev_b32_e32 v183, 16, v183
	v_lshlrev_b32_e32 v185, 16, v185
	v_rcp_f32_e32 v161, v19
	v_rcp_f32_e32 v162, v23
	v_mul_f32_e32 v19, v19, v183
	v_cvt_pk_bf16_f32 v19, v19, v177
	ds_write_b16 v109, v19
	v_mul_f32_e32 v19, v23, v185
	v_lshlrev_b32_e32 v184, 16, v184
	v_lshlrev_b32_e32 v186, 16, v186
	v_cvt_pk_bf16_f32 v19, v19, v177
	ds_write_b16 v109, v19 offset:272
	v_mul_f32_e32 v19, v161, v184
	v_mul_f32_e32 v23, v162, v186
	v_cvt_pk_bf16_f32 v161, v19, v177
	ds_write_b16 v109, v161 offset:17408
	v_cvt_pk_bf16_f32 v161, v23, v177
	v_mul_f32_e32 v19, v20, v19
	v_mul_f32_e32 v23, v20, v23
	ds_write_b16 v109, v161 offset:17680
	v_cvt_pk_bf16_f32 v19, v19, v23
	v_add_f32_e32 v23, v175, v221
	v_add_f32_e32 v161, v182, v221
	v_mul_f32_e32 v23, 0x3fb8aa3b, v23
	v_exp_f32_e32 v23, v23
	v_mul_f32_e32 v161, 0x3fb8aa3b, v161
	v_exp_f32_e32 v161, v161
	v_lshlrev_b32_e32 v187, 16, v187
	v_rcp_f32_e32 v162, v23
	v_mul_f32_e32 v23, v23, v187
	v_lshlrev_b32_e32 v189, 16, v189
	v_rcp_f32_e32 v163, v161
	v_cvt_pk_bf16_f32 v23, v23, v177
	ds_write_b16 v110, v23
	v_mul_f32_e32 v23, v161, v189
	v_lshlrev_b32_e32 v188, 16, v188
	v_cvt_pk_bf16_f32 v23, v23, v177
	v_lshlrev_b32_e32 v190, 16, v190
	ds_write_b16 v110, v23 offset:272
	v_mul_f32_e32 v23, v162, v188
	v_cvt_pk_bf16_f32 v162, v23, v177
	v_mul_f32_e32 v161, v163, v190
	ds_write_b16 v110, v162 offset:17408
	v_cvt_pk_bf16_f32 v162, v161, v177
	v_mul_f32_e32 v23, v20, v23
	ds_write_b16 v110, v162 offset:17680
	v_mul_f32_e32 v161, v20, v161
	v_cvt_pk_bf16_f32 v162, v23, v161
	v_add_f32_e32 v23, v165, v221
	v_add_f32_e32 v161, v166, v221
	v_mul_f32_e32 v23, 0x3fb8aa3b, v23
	v_exp_f32_e32 v23, v23
	v_mul_f32_e32 v161, 0x3fb8aa3b, v161
	v_exp_f32_e32 v161, v161
	v_lshlrev_b32_e32 v193, 16, v193
	v_rcp_f32_e32 v163, v23
	v_mul_f32_e32 v23, v23, v193
	v_lshlrev_b32_e32 v195, 16, v195
	v_rcp_f32_e32 v164, v161
	v_cvt_pk_bf16_f32 v23, v23, v177
	ds_write_b16 v111, v23
	v_mul_f32_e32 v23, v161, v195
	v_lshlrev_b32_e32 v194, 16, v194
	v_cvt_pk_bf16_f32 v23, v23, v177
	v_lshlrev_b32_e32 v196, 16, v196
	ds_write_b16 v111, v23 offset:272
	v_mul_f32_e32 v23, v163, v194
	v_cvt_pk_bf16_f32 v163, v23, v177
	v_mul_f32_e32 v161, v164, v196
	ds_write_b16 v111, v163 offset:17408
	v_cvt_pk_bf16_f32 v163, v161, v177
	v_mul_f32_e32 v23, v20, v23
	ds_write_b16 v111, v163 offset:17680
	v_mul_f32_e32 v161, v20, v161
	v_cvt_pk_bf16_f32 v163, v23, v161
	v_add_f32_e32 v23, v159, v221
	v_add_f32_e32 v159, v160, v221
	v_mul_f32_e32 v23, 0x3fb8aa3b, v23
	v_mul_f32_e32 v159, 0x3fb8aa3b, v159
	v_exp_f32_e32 v23, v23
	v_exp_f32_e32 v159, v159
	v_lshlrev_b32_e32 v197, 16, v197
	v_add_f32_e32 v21, v21, v221
	v_rcp_f32_e32 v160, v23
	v_rcp_f32_e32 v161, v159
	v_mul_f32_e32 v23, v23, v197
	v_add_f32_e32 v22, v22, v221
	v_lshlrev_b32_e32 v199, 16, v199
	v_cvt_pk_bf16_f32 v23, v23, v177
	v_mul_f32_e32 v21, 0x3fb8aa3b, v21
	v_mul_f32_e32 v22, 0x3fb8aa3b, v22
	ds_write_b16 v112, v23
	v_mul_f32_e32 v23, v159, v199
	v_exp_f32_e32 v21, v21
	v_exp_f32_e32 v22, v22
	v_lshlrev_b32_e32 v198, 16, v198
	v_lshlrev_b32_e32 v200, 16, v200
	v_cvt_pk_bf16_f32 v23, v23, v177
	ds_write_b16 v112, v23 offset:272
	v_mul_f32_e32 v23, v160, v198
	v_mul_f32_e32 v159, v161, v200
	v_cvt_pk_bf16_f32 v160, v23, v177
	v_lshlrev_b32_e32 v214, 16, v214
	ds_write_b16 v112, v160 offset:17408
	v_cvt_pk_bf16_f32 v160, v159, v177
	v_mul_f32_e32 v23, v20, v23
	v_mul_f32_e32 v159, v20, v159
	ds_write_b16 v112, v160 offset:17680
	v_cvt_pk_bf16_f32 v164, v23, v159
	v_rcp_f32_e32 v23, v21
	v_rcp_f32_e32 v159, v22
	v_mul_f32_e32 v21, v21, v214
	v_lshlrev_b32_e32 v216, 16, v216
	v_cvt_pk_bf16_f32 v21, v21, v177
	ds_write_b16 v113, v21
	v_mul_f32_e32 v21, v22, v216
	v_lshlrev_b32_e32 v215, 16, v215
	v_lshlrev_b32_e32 v217, 16, v217
	v_cvt_pk_bf16_f32 v21, v21, v177
	ds_write_b16 v113, v21 offset:272
	v_mul_f32_e32 v21, v23, v215
	v_mul_f32_e32 v22, v159, v217
	v_cvt_pk_bf16_f32 v23, v21, v177
	ds_write_b16 v113, v23 offset:17408
	v_cvt_pk_bf16_f32 v23, v22, v177
	ds_write_b16 v113, v23 offset:17680
	v_mul_f32_e32 v21, v20, v21
	v_mul_f32_e32 v20, v20, v22
	v_cvt_pk_bf16_f32 v165, v21, v20
	ds_write_b128 v125, v[16:19] offset:34816
	ds_write_b128 v125, v[162:165] offset:34832
	v_cvt_pk_bf16_f32 v16, v0, v1
	v_cvt_pk_bf16_f32 v17, v2, v3
	ds_write_b64 v126, v[16:17]
	v_cvt_pk_bf16_f32 v16, v4, v5
	v_cvt_pk_bf16_f32 v17, v6, v7
	ds_write_b64 v126, v[16:17] offset:4352
	v_cvt_pk_bf16_f32 v16, v8, v9
	v_cvt_pk_bf16_f32 v17, v10, v11
	ds_write_b64 v126, v[16:17] offset:8704
	v_cvt_pk_bf16_f32 v16, v12, v13
	v_cvt_pk_bf16_f32 v17, v14, v15
	ds_write_b64 v126, v[16:17] offset:13056
	s_waitcnt lgkmcnt(0)
	s_barrier
	ds_read_b128 v[186:189], v30
	ds_read_b128 v[164:167], v114 offset:17408
	ds_read_b128 v[168:171], v115
	ds_read_b128 v[172:175], v116 offset:17408
	ds_read_b128 v[236:239], v117
	ds_read_b128 v[222:225], v128
	ds_read_b128 v[190:193], v30 offset:64
	ds_read_b128 v[240:243], v114 offset:17472
	ds_read_b128 v[244:247], v115 offset:64
	ds_read_b128 v[214:217], v116 offset:17472
	ds_read_b128 v[218:221], v117 offset:64
	ds_read_b128 v[194:197], v30 offset:128
	ds_read_b128 v[198:201], v30 offset:192
	s_sub_i32 s31, s31, 64
	s_add_i32 s29, s29, 64
	s_cmpk_eq_i32 s31, 0xffc0
	s_waitcnt lgkmcnt(11)
	v_mfma_f32_16x16x32_bf16 v[182:185], v[186:189], v[164:167], 0
	s_waitcnt lgkmcnt(10)
	v_mfma_f32_16x16x32_bf16 v[16:19], v[186:189], v[168:171], 0
	s_waitcnt lgkmcnt(9)
	v_mfma_f32_16x16x32_bf16 v[160:163], v[186:189], v[172:175], 0
	s_waitcnt lgkmcnt(8)
	v_mfma_f32_16x16x32_bf16 v[20:23], v[186:189], v[236:239], 0
	s_waitcnt lgkmcnt(7)
	v_pk_mul_f32 v[0:1], v[0:1], v[222:223]
	v_pk_mul_f32 v[4:5], v[4:5], v[222:223]
	v_pk_mul_f32 v[8:9], v[8:9], v[222:223]
	v_pk_mul_f32 v[12:13], v[12:13], v[222:223]
	v_pk_mul_f32 v[2:3], v[2:3], v[224:225]
	v_pk_mul_f32 v[6:7], v[6:7], v[224:225]
	v_pk_mul_f32 v[10:11], v[10:11], v[224:225]
	v_pk_mul_f32 v[14:15], v[14:15], v[224:225]
	ds_read_b128 v[164:167], v114 offset:17536
	ds_read_b128 v[168:171], v115 offset:128
	ds_read_b128 v[172:175], v116 offset:17536
	ds_read_b128 v[236:239], v117 offset:128
	s_waitcnt lgkmcnt(9)
	v_mfma_f32_16x16x32_bf16 v[182:185], v[190:193], v[240:243], v[182:185]
	s_waitcnt lgkmcnt(8)
	v_mfma_f32_16x16x32_bf16 v[16:19], v[190:193], v[244:247], v[16:19]
	s_waitcnt lgkmcnt(7)
	v_mfma_f32_16x16x32_bf16 v[160:163], v[190:193], v[214:217], v[160:163]
	s_waitcnt lgkmcnt(6)
	v_mfma_f32_16x16x32_bf16 v[20:23], v[190:193], v[218:221], v[20:23]
	ds_read_b128 v[240:243], v114 offset:17600
	ds_read_b128 v[244:247], v115 offset:192
	ds_read_b128 v[214:217], v116 offset:17600
	ds_read_b128 v[218:221], v117 offset:192
	s_waitcnt lgkmcnt(7)
	v_mfma_f32_16x16x32_bf16 v[182:185], v[194:197], v[164:167], v[182:185]
	s_waitcnt lgkmcnt(6)
	v_mfma_f32_16x16x32_bf16 v[16:19], v[194:197], v[168:171], v[16:19]
	s_waitcnt lgkmcnt(5)
	v_mfma_f32_16x16x32_bf16 v[160:163], v[194:197], v[172:175], v[160:163]
	s_waitcnt lgkmcnt(4)
	v_mfma_f32_16x16x32_bf16 v[20:23], v[194:197], v[236:239], v[20:23]
	s_waitcnt lgkmcnt(3)
	v_mfma_f32_16x16x32_bf16 v[182:185], v[198:201], v[240:243], v[182:185]
	s_waitcnt lgkmcnt(2)
	v_mfma_f32_16x16x32_bf16 v[16:19], v[198:201], v[244:247], v[16:19]
	s_waitcnt lgkmcnt(1)
	v_mfma_f32_16x16x32_bf16 v[160:163], v[198:201], v[214:217], v[160:163]
	s_waitcnt lgkmcnt(0)
	v_mfma_f32_16x16x32_bf16 v[20:23], v[198:201], v[218:221], v[20:23]
	ds_read_b128 v[186:189], v32 offset:34816
	ds_read_b128 v[164:167], v129 offset:53248
	ds_read_b128 v[168:171], v129 offset:55552
	ds_read_b128 v[172:175], v129 offset:57856
	ds_read_b128 v[236:239], v129 offset:60160
	s_nop 1
	v_cndmask_b32_e64 v159, v182, 0, s[12:13]
	v_cvt_pk_bf16_f32 v159, v159, v177
	ds_write_b16 v127, v159 offset:62464
	v_cndmask_b32_e64 v159, v183, 0, s[14:15]
	v_cvt_pk_bf16_f32 v159, v159, v177
	ds_write_b16 v127, v159 offset:62608
	v_cndmask_b32_e64 v159, v184, 0, s[16:17]
	v_cvt_pk_bf16_f32 v159, v159, v177
	ds_write_b16 v127, v159 offset:62752
	v_cndmask_b32_e64 v159, v185, 0, s[18:19]
	v_cvt_pk_bf16_f32 v159, v159, v177
	ds_write_b16 v127, v159 offset:62896
	v_cndmask_b32_e64 v159, v160, 0, s[20:21]
	v_cvt_pk_bf16_f32 v159, v159, v177
	ds_write_b16 v127, v159 offset:62496
	v_cndmask_b32_e64 v159, v161, 0, s[22:23]
	v_cvt_pk_bf16_f32 v159, v159, v177
	ds_write_b16 v127, v159 offset:62640
	v_cndmask_b32_e64 v159, v162, 0, s[24:25]
	v_cvt_pk_bf16_f32 v159, v159, v177
	ds_write_b16 v127, v159 offset:62784
	v_cndmask_b32_e64 v159, v163, 0, s[38:39]
	v_cvt_pk_bf16_f32 v159, v159, v177
	ds_write_b16 v127, v159 offset:62928
	s_waitcnt lgkmcnt(8)
	ds_read_b128 v[190:193], v32 offset:34880
	ds_read_b128 v[240:243], v129 offset:53312
	ds_read_b128 v[244:247], v129 offset:55616
	ds_read_b128 v[214:217], v129 offset:57920
	ds_read_b128 v[218:221], v129 offset:60224
	v_mfma_f32_16x16x32_bf16 v[0:3], v[186:189], v[164:167], v[0:3]
	v_mfma_f32_16x16x32_bf16 v[4:7], v[186:189], v[168:171], v[4:7]
	v_mfma_f32_16x16x32_bf16 v[8:11], v[186:189], v[172:175], v[8:11]
	v_mfma_f32_16x16x32_bf16 v[12:15], v[186:189], v[236:239], v[12:15]
	s_waitcnt lgkmcnt(3)
	v_mfma_f32_16x16x32_bf16 v[0:3], v[190:193], v[240:243], v[0:3]
	s_waitcnt lgkmcnt(2)
	v_mfma_f32_16x16x32_bf16 v[4:7], v[190:193], v[244:247], v[4:7]
	s_waitcnt lgkmcnt(1)
	v_mfma_f32_16x16x32_bf16 v[8:11], v[190:193], v[214:217], v[8:11]
	s_waitcnt lgkmcnt(0)
	s_barrier
	v_mfma_f32_16x16x32_bf16 v[12:15], v[190:193], v[218:221], v[12:15]
	ds_read_b128 v[160:163], v33 offset:62464
	ds_read_b128 v[164:167], v130 offset:53248
	ds_read_b128 v[168:171], v131 offset:53248
	ds_read_b128 v[172:175], v33 offset:62528
	ds_read_b128 v[236:239], v130 offset:53312
	ds_read_b128 v[240:243], v131 offset:53312
	s_waitcnt lgkmcnt(4)
	v_mfma_f32_16x16x32_bf16 v[16:19], v[160:163], v[164:167], v[16:19]
	s_waitcnt lgkmcnt(3)
	v_mfma_f32_16x16x32_bf16 v[20:23], v[160:163], v[168:171], v[20:23]
	s_waitcnt lgkmcnt(1)
	v_mfma_f32_16x16x32_bf16 v[16:19], v[172:175], v[236:239], v[16:19]
	s_waitcnt lgkmcnt(0)
	v_mfma_f32_16x16x32_bf16 v[20:23], v[172:175], v[240:243], v[20:23]
	v_add_u32_e32 v160, s33, v132
	v_ashrrev_i32_e32 v161, 31, v160
	v_add_u32_e32 v162, s33, v47
	v_lshlrev_b64 v[160:161], 10, v[160:161]
	v_ashrrev_i32_e32 v163, 31, v162
	v_lshl_add_u64 v[160:161], v[52:53], 0, v[160:161]
	v_lshlrev_b64 v[162:163], 10, v[162:163]
	global_store_dword v[160:161], v16, off
	v_lshl_add_u64 v[162:163], v[52:53], 0, v[162:163]
	v_add_u32_e32 v16, s33, v157
	v_add_u32_e32 v164, s33, v158
	global_store_dword v[162:163], v17, off
	v_ashrrev_i32_e32 v17, 31, v16
	v_ashrrev_i32_e32 v165, 31, v164
	v_lshlrev_b64 v[16:17], 10, v[16:17]
	v_lshlrev_b64 v[164:165], 10, v[164:165]
	v_lshl_add_u64 v[16:17], v[52:53], 0, v[16:17]
	v_lshl_add_u64 v[164:165], v[52:53], 0, v[164:165]
	global_store_dword v[16:17], v18, off
	global_store_dword v[164:165], v19, off
	global_store_dword v[160:161], v20, off offset:64
	global_store_dword v[162:163], v21, off offset:64
	global_store_dword v[16:17], v22, off offset:64
	global_store_dword v[164:165], v23, off offset:64
	s_barrier
	s_cbranch_scc1 .LBB0_294

.LBB0_310:
	s_or_b64 exec, exec, s[2:3]
	v_cndmask_b32_e64 v18, 0, v18, s[6:7]
	v_add_f32_e32 v19, v19, v18
	v_cndmask_b32_e64 v18, v18, v19, s[8:9]
	v_add_f32_e32 v16, v16, v18
	v_cndmask_b32_e64 v16, v18, v16, s[10:11]
	v_add_f32_e32 v17, v17, v16
	v_cndmask_b32_e64 v153, v16, v17, s[12:13]
	v_add_f32_e32 v16, v153, v120
	v_add_f32_e32 v17, v152, v153
	v_sub_f32_e32 v16, v127, v16
	v_sub_f32_e32 v17, v127, v17
	v_mul_f32_e32 v16, 0x3fb8aa3b, v16
	v_mul_f32_e32 v17, 0x3fb8aa3b, v17
	v_exp_f32_e32 v16, v16
	v_exp_f32_e32 v17, v17
	v_lshlrev_b32_e32 v121, 16, v121
	v_lshlrev_b32_e32 v122, 16, v122
	v_mul_f32_e32 v16, v16, v121
	v_mul_f32_e32 v17, v17, v122
	v_cvt_pk_bf16_f32 v16, v16, v17
	v_add_f32_e32 v17, v150, v153
	v_add_f32_e32 v18, v151, v153
	v_sub_f32_e32 v17, v127, v17
	v_sub_f32_e32 v18, v127, v18
	v_mul_f32_e32 v17, 0x3fb8aa3b, v17
	v_mul_f32_e32 v18, 0x3fb8aa3b, v18
	v_exp_f32_e32 v17, v17
	v_exp_f32_e32 v18, v18
	v_lshlrev_b32_e32 v123, 16, v123
	v_lshlrev_b32_e32 v126, 16, v126
	v_mul_f32_e32 v17, v17, v123
	v_mul_f32_e32 v18, v18, v126
	v_cvt_pk_bf16_f32 v17, v17, v18
	v_add_f32_e32 v18, v147, v153
	v_add_f32_e32 v19, v148, v153
	v_sub_f32_e32 v18, v127, v18
	v_sub_f32_e32 v19, v127, v19
	v_mul_f32_e32 v18, 0x3fb8aa3b, v18
	v_mul_f32_e32 v19, 0x3fb8aa3b, v19
	v_exp_f32_e32 v18, v18
	v_exp_f32_e32 v19, v19
	v_lshlrev_b32_e32 v128, 16, v128
	v_lshlrev_b32_e32 v131, 16, v131
	v_mul_f32_e32 v18, v18, v128
	v_mul_f32_e32 v19, v19, v131
	v_cvt_pk_bf16_f32 v18, v18, v19
	v_add_f32_e32 v19, v143, v153
	v_add_f32_e32 v120, v144, v153
	v_sub_f32_e32 v19, v127, v19
	v_sub_f32_e32 v120, v127, v120
	v_mul_f32_e32 v19, 0x3fb8aa3b, v19
	v_mul_f32_e32 v120, 0x3fb8aa3b, v120
	v_exp_f32_e32 v19, v19
	v_exp_f32_e32 v120, v120
	v_lshlrev_b32_e32 v132, 16, v132
	v_lshlrev_b32_e32 v133, 16, v133
	v_mul_f32_e32 v19, v19, v132
	v_mul_f32_e32 v120, v120, v133
	v_cvt_pk_bf16_f32 v19, v19, v120
	v_add_f32_e32 v120, v138, v153
	v_add_f32_e32 v121, v139, v153
	v_sub_f32_e32 v120, v127, v120
	v_sub_f32_e32 v121, v127, v121
	v_mul_f32_e32 v120, 0x3fb8aa3b, v120
	v_mul_f32_e32 v121, 0x3fb8aa3b, v121
	v_exp_f32_e32 v120, v120
	v_exp_f32_e32 v121, v121
	v_lshlrev_b32_e32 v136, 16, v136
	v_lshlrev_b32_e32 v137, 16, v137
	v_mul_f32_e32 v120, v120, v136
	v_mul_f32_e32 v121, v121, v137
	v_cvt_pk_bf16_f32 v120, v120, v121
	v_add_f32_e32 v121, v134, v153
	v_add_f32_e32 v122, v135, v153
	v_sub_f32_e32 v121, v127, v121
	v_sub_f32_e32 v122, v127, v122
	v_mul_f32_e32 v121, 0x3fb8aa3b, v121
	v_mul_f32_e32 v122, 0x3fb8aa3b, v122
	v_exp_f32_e32 v121, v121
	v_exp_f32_e32 v122, v122
	v_lshlrev_b32_e32 v140, 16, v140
	v_lshlrev_b32_e32 v141, 16, v141
	v_mul_f32_e32 v121, v121, v140
	v_mul_f32_e32 v122, v122, v141
	v_cvt_pk_bf16_f32 v121, v121, v122
	v_add_f32_e32 v122, v129, v153
	v_add_f32_e32 v123, v130, v153
	v_sub_f32_e32 v122, v127, v122
	v_sub_f32_e32 v123, v127, v123
	v_mul_f32_e32 v122, 0x3fb8aa3b, v122
	v_mul_f32_e32 v123, 0x3fb8aa3b, v123
	v_exp_f32_e32 v122, v122
	v_exp_f32_e32 v123, v123
	v_lshlrev_b32_e32 v142, 16, v142
	v_lshlrev_b32_e32 v145, 16, v145
	v_mul_f32_e32 v122, v122, v142
	v_mul_f32_e32 v123, v123, v145
	v_cvt_pk_bf16_f32 v122, v122, v123
	v_add_f32_e32 v123, v124, v153
	v_add_f32_e32 v124, v125, v153
	v_sub_f32_e32 v123, v127, v123
	v_mul_f32_e32 v123, 0x3fb8aa3b, v123
	v_sub_f32_e32 v124, v127, v124
	v_exp_f32_e32 v123, v123
	v_mul_f32_e32 v124, 0x3fb8aa3b, v124
	v_exp_f32_e32 v124, v124
	v_lshlrev_b32_e32 v146, 16, v146
	v_lshlrev_b32_e32 v149, 16, v149
	v_mul_f32_e32 v123, v123, v146
	v_mul_f32_e32 v124, v124, v149
	v_cvt_pk_bf16_f32 v123, v123, v124
	ds_write_b128 v93, v[16:19] offset:34816
	ds_write_b128 v93, v[120:123] offset:34832
	s_waitcnt lgkmcnt(0)
	s_barrier
	ds_read_b128 v[16:19], v95
	ds_read_b128 v[120:123], v24 offset:34816
	ds_read_b128 v[128:131], v94 offset:53248
	ds_read_b128 v[132:135], v94 offset:55552
	ds_read_b128 v[136:139], v94 offset:57856
	ds_read_b128 v[140:143], v94 offset:60160
	ds_read_b128 v[124:127], v24 offset:34880
	ds_read_b128 v[144:147], v94 offset:53312
	ds_read_b128 v[148:151], v94 offset:55616
	ds_read_b128 v[152:155], v94 offset:57920
	ds_read_b128 v[236:239], v94 offset:60224
	s_sub_i32 s25, s25, 64
	s_add_i32 s23, s23, 64
	s_cmpk_eq_i32 s25, 0xffc0
	s_waitcnt lgkmcnt(10)
	v_pk_mul_f32 v[0:1], v[0:1], v[16:17]
	v_pk_mul_f32 v[2:3], v[2:3], v[18:19]
	v_pk_mul_f32 v[4:5], v[4:5], v[16:17]
	v_pk_mul_f32 v[6:7], v[6:7], v[18:19]
	v_pk_mul_f32 v[8:9], v[8:9], v[16:17]
	v_pk_mul_f32 v[10:11], v[10:11], v[18:19]
	v_pk_mul_f32 v[12:13], v[12:13], v[16:17]
	v_pk_mul_f32 v[14:15], v[14:15], v[18:19]
	s_waitcnt lgkmcnt(8)
	v_mfma_f32_16x16x32_bf16 v[0:3], v[120:123], v[128:131], v[0:3]
	s_waitcnt lgkmcnt(7)
	v_mfma_f32_16x16x32_bf16 v[4:7], v[120:123], v[132:135], v[4:7]
	s_waitcnt lgkmcnt(6)
	v_mfma_f32_16x16x32_bf16 v[8:11], v[120:123], v[136:139], v[8:11]
	s_waitcnt lgkmcnt(5)
	v_mfma_f32_16x16x32_bf16 v[12:15], v[120:123], v[140:143], v[12:15]
	s_waitcnt lgkmcnt(3)
	v_mfma_f32_16x16x32_bf16 v[0:3], v[124:127], v[144:147], v[0:3]
	s_waitcnt lgkmcnt(2)
	v_mfma_f32_16x16x32_bf16 v[4:7], v[124:127], v[148:151], v[4:7]
	s_waitcnt lgkmcnt(1)
	v_mfma_f32_16x16x32_bf16 v[8:11], v[124:127], v[152:155], v[8:11]
	s_waitcnt lgkmcnt(0)
	s_barrier
	v_mfma_f32_16x16x32_bf16 v[12:15], v[124:127], v[236:239], v[12:15]
	s_cbranch_scc1 .LBB0_313
